# GLA scan state update: v_pk_mul_f32 decay scaling between MFMAs split into scalar v_mul (on top of attention-loop split)
# baseline (speedup 1.0000x reference)
.LBB0_423:
	s_nop 3
	ds_read_b128 v[196:199], v188 offset:17408
	ds_read_b128 v[200:203], v188 offset:17472
	v_mul_f32_e64 v4, v4, v182
	v_mul_f32_e64 v5, v5, v182
	v_mul_f32_e64 v2, v2, v182
	v_mul_f32_e64 v3, v3, v182
	v_mul_f32_e64 v8, v8, v180
	v_mul_f32_e64 v9, v9, v180
	v_mul_f32_e64 v6, v6, v180
	v_mul_f32_e64 v7, v7, v180
	s_waitcnt lgkmcnt(1)
	v_mfma_f32_16x16x32_bf16 v[2:5], v[86:89], v[196:199], v[2:5]
	ds_read_b128 v[196:199], v125 offset:17408
	v_mul_f32_e64 v20, v20, v178
	v_mul_f32_e64 v21, v21, v178
	v_mul_f32_e64 v18, v18, v178
	v_mul_f32_e64 v19, v19, v178
	s_waitcnt lgkmcnt(1)
	v_mfma_f32_16x16x32_bf16 v[2:5], v[82:85], v[200:203], v[2:5]
	ds_read_b128 v[200:203], v125 offset:17472
	v_mul_f32_e64 v12, v12, v176
	v_mul_f32_e64 v13, v13, v176
	v_mul_f32_e64 v10, v10, v176
	v_mul_f32_e64 v11, v11, v176
	s_waitcnt lgkmcnt(1)
	v_mfma_f32_16x16x32_bf16 v[6:9], v[86:89], v[196:199], v[6:9]
	ds_read_b128 v[196:199], v189 offset:17408
	v_mul_f32_e64 v24, v24, v174
	v_mul_f32_e64 v25, v25, v174
	v_mul_f32_e64 v22, v22, v174
	v_mul_f32_e64 v23, v23, v174
	s_waitcnt lgkmcnt(1)
	v_mfma_f32_16x16x32_bf16 v[6:9], v[82:85], v[200:203], v[6:9]
	ds_read_b128 v[200:203], v189 offset:17472
	ds_read_b128 v[174:177], v127 offset:17472
	v_mul_f32_e64 v16, v16, v172
	v_mul_f32_e64 v17, v17, v172
	s_waitcnt lgkmcnt(2)
	v_mfma_f32_16x16x32_bf16 v[18:21], v[86:89], v[196:199], v[18:21]
	ds_read_b128 v[196:199], v190 offset:17408
	v_mul_f32_e64 v14, v14, v172
	v_mul_f32_e64 v15, v15, v172
	v_mul_f32_e64 v28, v28, v170
	v_mul_f32_e64 v29, v29, v170
	s_waitcnt lgkmcnt(2)
	v_mfma_f32_16x16x32_bf16 v[18:21], v[82:85], v[200:203], v[18:21]
	ds_read_b128 v[200:203], v190 offset:17472
	v_mul_f32_e64 v26, v26, v170
	v_mul_f32_e64 v27, v27, v170
	v_mul_f32_e64 v32, v32, v168
	v_mul_f32_e64 v33, v33, v168
	s_waitcnt lgkmcnt(1)
	v_mfma_f32_16x16x32_bf16 v[10:13], v[86:89], v[196:199], v[10:13]
	ds_read_b128 v[196:199], v127 offset:17408
	v_mul_f32_e64 v30, v30, v168
	v_mul_f32_e64 v31, v31, v168
	s_add_i32 s62, s62, -1
	s_waitcnt lgkmcnt(0)
	v_mfma_f32_16x16x32_bf16 v[22:25], v[86:89], v[196:199], v[22:25]
	ds_read_b128 v[196:199], v129 offset:17408
	s_cmp_eq_u32 s60, s58
	v_mfma_f32_16x16x32_bf16 v[22:25], v[82:85], v[174:177], v[22:25]
	ds_read_b128 v[172:175], v129 offset:17472
	s_waitcnt lgkmcnt(1)
	v_mfma_f32_16x16x32_bf16 v[14:17], v[86:89], v[196:199], v[14:17]
	ds_read_b128 v[196:199], v131 offset:17408
	s_waitcnt lgkmcnt(1)
	v_mfma_f32_16x16x32_bf16 v[14:17], v[82:85], v[172:175], v[14:17]
	ds_read_b128 v[170:173], v131 offset:17472
	ds_read_b128 v[174:177], v187 offset:17408
	s_waitcnt lgkmcnt(2)
	v_mfma_f32_16x16x32_bf16 v[26:29], v[86:89], v[196:199], v[26:29]
	s_waitcnt lgkmcnt(1)
	v_mfma_f32_16x16x32_bf16 v[26:29], v[82:85], v[170:173], v[26:29]
	ds_read_b128 v[168:171], v187 offset:17472
	s_waitcnt lgkmcnt(1)
	v_mfma_f32_16x16x32_bf16 v[30:33], v[86:89], v[174:177], v[30:33]
	v_mfma_f32_16x16x32_bf16 v[10:13], v[82:85], v[200:203], v[10:13]
	s_waitcnt lgkmcnt(0)
	v_mfma_f32_16x16x32_bf16 v[30:33], v[82:85], v[168:171], v[30:33]
	s_cbranch_scc1 .LBB0_430

.LBB0_1163:
	s_nop 3
	ds_read_b128 v[192:195], v183 offset:17408
	ds_read_b128 v[196:199], v183 offset:17472
	v_mul_f32_e64 v4, v4, v184
	v_mul_f32_e64 v5, v5, v184
	v_mul_f32_e64 v2, v2, v184
	v_mul_f32_e64 v3, v3, v184
	v_mul_f32_e64 v8, v8, v182
	v_mul_f32_e64 v9, v9, v182
	v_mul_f32_e64 v6, v6, v182
	v_mul_f32_e64 v7, v7, v182
	s_waitcnt lgkmcnt(1)
	v_mfma_f32_16x16x32_bf16 v[2:5], v[86:89], v[192:195], v[2:5]
	ds_read_b128 v[192:195], v125 offset:17408
	v_mul_f32_e64 v20, v20, v180
	v_mul_f32_e64 v21, v21, v180
	v_mul_f32_e64 v18, v18, v180
	v_mul_f32_e64 v19, v19, v180
	s_waitcnt lgkmcnt(1)
	v_mfma_f32_16x16x32_bf16 v[2:5], v[82:85], v[196:199], v[2:5]
	ds_read_b128 v[196:199], v125 offset:17472
	v_mul_f32_e64 v12, v12, v178
	v_mul_f32_e64 v13, v13, v178
	v_mul_f32_e64 v10, v10, v178
	v_mul_f32_e64 v11, v11, v178
	s_waitcnt lgkmcnt(1)
	v_mfma_f32_16x16x32_bf16 v[6:9], v[86:89], v[192:195], v[6:9]
	ds_read_b128 v[192:195], v185 offset:17408
	v_mul_f32_e64 v24, v24, v176
	v_mul_f32_e64 v25, v25, v176
	v_mul_f32_e64 v22, v22, v176
	v_mul_f32_e64 v23, v23, v176
	s_waitcnt lgkmcnt(1)
	v_mfma_f32_16x16x32_bf16 v[6:9], v[82:85], v[196:199], v[6:9]
	ds_read_b128 v[196:199], v185 offset:17472
	ds_read_b128 v[176:179], v127 offset:17472
	v_mul_f32_e64 v16, v16, v174
	v_mul_f32_e64 v17, v17, v174
	s_waitcnt lgkmcnt(2)
	v_mfma_f32_16x16x32_bf16 v[18:21], v[86:89], v[192:195], v[18:21]
	ds_read_b128 v[192:195], v186 offset:17408
	v_mul_f32_e64 v14, v14, v174
	v_mul_f32_e64 v15, v15, v174
	v_mul_f32_e64 v28, v28, v172
	v_mul_f32_e64 v29, v29, v172
	s_waitcnt lgkmcnt(2)
	v_mfma_f32_16x16x32_bf16 v[18:21], v[82:85], v[196:199], v[18:21]
	ds_read_b128 v[196:199], v186 offset:17472
	v_mul_f32_e64 v26, v26, v172
	v_mul_f32_e64 v27, v27, v172
	v_mul_f32_e64 v32, v32, v170
	v_mul_f32_e64 v33, v33, v170
	s_waitcnt lgkmcnt(1)
	v_mfma_f32_16x16x32_bf16 v[10:13], v[86:89], v[192:195], v[10:13]
	ds_read_b128 v[192:195], v127 offset:17408
	v_mul_f32_e64 v30, v30, v170
	v_mul_f32_e64 v31, v31, v170
	s_add_i32 s60, s60, -1
	s_waitcnt lgkmcnt(0)
	v_mfma_f32_16x16x32_bf16 v[22:25], v[86:89], v[192:195], v[22:25]
	ds_read_b128 v[192:195], v129 offset:17408
	s_cmp_eq_u32 s58, s56
	v_mfma_f32_16x16x32_bf16 v[22:25], v[82:85], v[176:179], v[22:25]
	ds_read_b128 v[174:177], v129 offset:17472
	s_waitcnt lgkmcnt(1)
	v_mfma_f32_16x16x32_bf16 v[14:17], v[86:89], v[192:195], v[14:17]
	ds_read_b128 v[192:195], v133 offset:17408
	s_waitcnt lgkmcnt(1)
	v_mfma_f32_16x16x32_bf16 v[14:17], v[82:85], v[174:177], v[14:17]
	ds_read_b128 v[172:175], v133 offset:17472
	ds_read_b128 v[176:179], v181 offset:17408
	s_waitcnt lgkmcnt(2)
	v_mfma_f32_16x16x32_bf16 v[26:29], v[86:89], v[192:195], v[26:29]
	s_waitcnt lgkmcnt(1)
	v_mfma_f32_16x16x32_bf16 v[26:29], v[82:85], v[172:175], v[26:29]
	ds_read_b128 v[170:173], v181 offset:17472
	s_waitcnt lgkmcnt(1)
	v_mfma_f32_16x16x32_bf16 v[30:33], v[86:89], v[176:179], v[30:33]
	v_mfma_f32_16x16x32_bf16 v[10:13], v[82:85], v[196:199], v[10:13]
	s_waitcnt lgkmcnt(0)
	v_mfma_f32_16x16x32_bf16 v[30:33], v[82:85], v[170:173], v[30:33]
	s_cbranch_scc1 .LBB0_1170
